# grid barrier: only the last-arriving workgroup of each XCD issues the L2 writeback (per-XCD arrival counters, XCC_ID)
# speedup vs baseline: 1.0643x; 1.0609x over previous
; DEVI int opaque_tid(int wv) { int t; asm volatile("v_mbcnt_lo_u32_b32 %0, -1, 0\n\tv_mbcnt_hi_u32_b32 %0, -1, %0" : "=v"(t)); return wv * 64 + t; }
; DEVI void gbar(unsigned* ctr, unsigned& gen, int wv) {
;   asm volatile("s_waitcnt vmcnt(0) lgkmcnt(0)" ::: "memory");
;   __syncthreads();
;   ++gen;
;   const int tb = opaque_tid(wv);
;   if (tb < 64) {
;     __builtin_amdgcn_fence(__ATOMIC_RELEASE, "agent");
;     asm volatile("s_waitcnt vmcnt(0)" ::: "memory");
;     if (tb == 0) {
;       __hip_atomic_fetch_add(ctr, 1u, __ATOMIC_RELAXED, __HIP_MEMORY_SCOPE_AGENT);
;       const unsigned target = gen * 256u;
;       while (__hip_atomic_load(ctr, __ATOMIC_RELAXED, __HIP_MEMORY_SCOPE_AGENT) < target) { }
;     }
;     __builtin_amdgcn_fence(__ATOMIC_ACQUIRE, "agent");
;     asm volatile("s_waitcnt vmcnt(0)" ::: "memory");
;   }
;   __syncthreads();
.LBB0_243:
	s_or_b64 exec, exec, s[0:1]
	v_readlane_b32 s0, v252, 40
	v_readlane_b32 s2, v252, 42
	s_waitcnt vmcnt(0) lgkmcnt(0)
	s_barrier
	v_mbcnt_lo_u32_b32 v0, -1, 0
	v_mbcnt_hi_u32_b32 v0, -1, v0
	v_readlane_b32 s0, v252, 46
	v_readlane_b32 s3, v252, 43
	s_add_u32 s52, s2, 0x1f414000
	v_add_u32_e32 v0, s0, v0
	v_readlane_b32 s1, v252, 41
	s_addc_u32 s53, s3, 0
	v_cmp_gt_i32_e32 vcc, 64, v0
	s_and_saveexec_b64 s[0:1], vcc
	s_cbranch_execz .LBB0_250
	s_waitcnt vmcnt(0)
	v_cmp_eq_u32_e32 vcc, 0, v0
	s_and_saveexec_b64 s[2:3], vcc
	s_cbranch_execz .LBB0_249
	s_getreg_b32 s6, hwreg(HW_REG_XCC_ID, 0, 4)
	s_lshl_b32 s6, s6, 2
	s_add_u32 s6, s52, s6
	s_addc_u32 s7, s53, 0
	v_mov_b32_e32 v0, 0
	v_mov_b32_e32 v1, 1
	global_atomic_add v1, v0, v1, s[6:7] offset:128 sc0
	s_waitcnt vmcnt(0)
	v_readfirstlane_b32 s4, v1
	s_cmp_lg_u32 s4, 31
	s_cbranch_scc1 .Lgb0_poll
	buffer_wbl2 sc1
	s_waitcnt vmcnt(0)
	v_mov_b32_e32 v1, 1
	global_atomic_add v0, v1, s[52:53]
.Lgb0_poll:
	s_movk_i32 s4, 8

; DEVI int opaque_tid(int wv) { int t; asm volatile("v_mbcnt_lo_u32_b32 %0, -1, 0\n\tv_mbcnt_hi_u32_b32 %0, -1, %0" : "=v"(t)); return wv * 64 + t; }
; DEVI void gbar(unsigned* ctr, unsigned& gen, int wv) {
;   asm volatile("s_waitcnt vmcnt(0) lgkmcnt(0)" ::: "memory");
;   __syncthreads();
;   ++gen;
;   const int tb = opaque_tid(wv);
;   if (tb < 64) {
;     __builtin_amdgcn_fence(__ATOMIC_RELEASE, "agent");
;     asm volatile("s_waitcnt vmcnt(0)" ::: "memory");
;     if (tb == 0) {
;       __hip_atomic_fetch_add(ctr, 1u, __ATOMIC_RELAXED, __HIP_MEMORY_SCOPE_AGENT);
;       const unsigned target = gen * 256u;
;       while (__hip_atomic_load(ctr, __ATOMIC_RELAXED, __HIP_MEMORY_SCOPE_AGENT) < target) { }
;     }
;     __builtin_amdgcn_fence(__ATOMIC_ACQUIRE, "agent");
;     asm volatile("s_waitcnt vmcnt(0)" ::: "memory");
;   }
;   __syncthreads();
.LBB0_615:
	s_barrier
	s_waitcnt vmcnt(0) lgkmcnt(0)
	s_barrier
	v_mbcnt_lo_u32_b32 v0, -1, 0
	v_mbcnt_hi_u32_b32 v0, -1, v0
	v_readlane_b32 s0, v252, 46
	s_nop 1
	v_add_u32_e32 v0, s0, v0
	v_cmp_gt_i32_e32 vcc, 64, v0
	s_and_saveexec_b64 s[0:1], vcc
	s_cbranch_execz .LBB0_622
	s_waitcnt vmcnt(0)
	v_cmp_eq_u32_e32 vcc, 0, v0
	s_and_saveexec_b64 s[4:5], vcc
	s_cbranch_execz .LBB0_621
	s_getreg_b32 s8, hwreg(HW_REG_XCC_ID, 0, 4)
	s_lshl_b32 s8, s8, 2
	s_add_u32 s8, s52, s8
	s_addc_u32 s9, s53, 0
	v_mov_b32_e32 v0, 1
	global_atomic_add v0, v33, v0, s[8:9] offset:128 sc0
	v_readlane_b32 s2, v254, 48
	s_lshl_b32 s2, s2, 5
	s_addk_i32 s2, 32
	s_waitcnt vmcnt(0)
	v_readfirstlane_b32 s6, v0
	s_add_i32 s6, s6, 1
	s_cmp_lg_u32 s6, s2
	s_cbranch_scc1 .Lgb1_poll
	buffer_wbl2 sc1
	s_waitcnt vmcnt(0)
	v_mov_b32_e32 v0, 1
	global_atomic_add v33, v0, s[52:53]
.Lgb1_poll:
	s_lshr_b32 s2, s2, 2

; DEVI int opaque_tid(int wv) { int t; asm volatile("v_mbcnt_lo_u32_b32 %0, -1, 0\n\tv_mbcnt_hi_u32_b32 %0, -1, %0" : "=v"(t)); return wv * 64 + t; }
; DEVI void gbar(unsigned* ctr, unsigned& gen, int wv) {
;   asm volatile("s_waitcnt vmcnt(0) lgkmcnt(0)" ::: "memory");
;   __syncthreads();
;   ++gen;
;   const int tb = opaque_tid(wv);
;   if (tb < 64) {
;     __builtin_amdgcn_fence(__ATOMIC_RELEASE, "agent");
;     asm volatile("s_waitcnt vmcnt(0)" ::: "memory");
;     if (tb == 0) {
;       __hip_atomic_fetch_add(ctr, 1u, __ATOMIC_RELAXED, __HIP_MEMORY_SCOPE_AGENT);
;       const unsigned target = gen * 256u;
;       while (__hip_atomic_load(ctr, __ATOMIC_RELAXED, __HIP_MEMORY_SCOPE_AGENT) < target) { }
;     }
;     __builtin_amdgcn_fence(__ATOMIC_ACQUIRE, "agent");
;     asm volatile("s_waitcnt vmcnt(0)" ::: "memory");
;   }
;   __syncthreads();
.LBB0_988:
	s_waitcnt vmcnt(0) lgkmcnt(0)
	s_barrier
	v_mbcnt_lo_u32_b32 v0, -1, 0
	v_mbcnt_hi_u32_b32 v0, -1, v0
	v_readlane_b32 s0, v252, 46
	s_nop 1
	v_add_u32_e32 v0, s0, v0
	v_cmp_gt_i32_e32 vcc, 64, v0
	s_and_saveexec_b64 s[0:1], vcc
	s_cbranch_execz .LBB0_995
	s_waitcnt vmcnt(0)
	v_cmp_eq_u32_e32 vcc, 0, v0
	s_and_saveexec_b64 s[4:5], vcc
	s_cbranch_execz .LBB0_994
	s_getreg_b32 s10, hwreg(HW_REG_XCC_ID, 0, 4)
	s_lshl_b32 s10, s10, 2
	s_add_u32 s10, s52, s10
	s_addc_u32 s11, s53, 0
	v_mov_b32_e32 v0, 1
	global_atomic_add v0, v33, v0, s[10:11] offset:128 sc0
	v_readlane_b32 s2, v254, 48
	s_lshl_b32 s2, s2, 5
	s_addk_i32 s2, 64
	s_waitcnt vmcnt(0)
	v_readfirstlane_b32 s6, v0
	s_add_i32 s6, s6, 1
	s_cmp_lg_u32 s6, s2
	s_cbranch_scc1 .Lgb2_poll
	buffer_wbl2 sc1
	s_waitcnt vmcnt(0)
	v_mov_b32_e32 v0, 1
	global_atomic_add v33, v0, s[52:53]

; DEVI int opaque_tid(int wv) { int t; asm volatile("v_mbcnt_lo_u32_b32 %0, -1, 0\n\tv_mbcnt_hi_u32_b32 %0, -1, %0" : "=v"(t)); return wv * 64 + t; }
; DEVI void gbar(unsigned* ctr, unsigned& gen, int wv) {
;   asm volatile("s_waitcnt vmcnt(0) lgkmcnt(0)" ::: "memory");
;   __syncthreads();
;   ++gen;
;   const int tb = opaque_tid(wv);
;   if (tb < 64) {
;     __builtin_amdgcn_fence(__ATOMIC_RELEASE, "agent");
;     asm volatile("s_waitcnt vmcnt(0)" ::: "memory");
;     if (tb == 0) {
;       __hip_atomic_fetch_add(ctr, 1u, __ATOMIC_RELAXED, __HIP_MEMORY_SCOPE_AGENT);
;       const unsigned target = gen * 256u;
;       while (__hip_atomic_load(ctr, __ATOMIC_RELAXED, __HIP_MEMORY_SCOPE_AGENT) < target) { }
;     }
;     __builtin_amdgcn_fence(__ATOMIC_ACQUIRE, "agent");
;     asm volatile("s_waitcnt vmcnt(0)" ::: "memory");
;   }
;   __syncthreads();
.LBB0_1496:
	s_waitcnt vmcnt(0) lgkmcnt(0)
	s_barrier
	v_mbcnt_lo_u32_b32 v0, -1, 0
	v_mbcnt_hi_u32_b32 v0, -1, v0
	v_readlane_b32 s0, v252, 46
	s_nop 1
	v_add_u32_e32 v0, s0, v0
	v_cmp_gt_i32_e32 vcc, 64, v0
	s_mov_b64 s[0:1], exec
	v_readlane_b32 s76, v253, 4
	v_readlane_b32 s77, v253, 5
	v_readlane_b32 s52, v255, 1
	v_readlane_b32 s54, v253, 22
	v_readlane_b32 s56, v253, 24
	s_and_b64 s[2:3], s[0:1], vcc
	v_readlane_b32 s53, v255, 2
	v_readlane_b32 s55, v253, 23
	v_readlane_b32 s57, v253, 25
	v_readlane_b32 s65, v255, 3
	s_movk_i32 s74, 0xffc0
	v_readlane_b32 s59, v255, 4
	v_readlane_b32 s64, v255, 5
	s_movk_i32 s75, 0x2ff
	s_mov_b32 s77, 0x800000
	s_mov_b32 s78, 0xfffe4000
	s_mov_b32 s79, 0xfffe8000
	s_mov_b32 s80, 0xfffec000
	s_mov_b32 s81, 0xffff0000
	s_mov_b32 s82, 0xffff4000
	s_movk_i32 s83, 0x8000
	s_movk_i32 s84, 0xc000
	s_movk_i32 s70, 0x140
	s_movk_i32 s85, 0xa000
	s_movk_i32 s86, 0xb000
	s_movk_i32 s87, 0xe000
	s_mov_b64 exec, s[2:3]
	s_cbranch_execz .LBB0_1503
	s_waitcnt vmcnt(0)
	v_cmp_eq_u32_e32 vcc, 0, v0
	s_and_saveexec_b64 s[4:5], vcc
	s_cbranch_execz .LBB0_1502
	s_getreg_b32 s8, hwreg(HW_REG_XCC_ID, 0, 4)
	s_lshl_b32 s8, s8, 2
	s_add_u32 s8, s52, s8
	s_addc_u32 s9, s53, 0
	v_mov_b32_e32 v0, 1
	global_atomic_add v0, v33, v0, s[8:9] offset:128 sc0
	v_readlane_b32 s2, v254, 48
	s_lshl_b32 s2, s2, 5
	s_addk_i32 s2, 96
	s_waitcnt vmcnt(0)
	v_readfirstlane_b32 s6, v0
	s_add_i32 s6, s6, 1
	s_cmp_lg_u32 s6, s2
	s_cbranch_scc1 .Lgb3_poll
	buffer_wbl2 sc1
	s_waitcnt vmcnt(0)
	v_mov_b32_e32 v0, 1
	global_atomic_add v33, v0, s[52:53]

; DEVI int opaque_tid(int wv) { int t; asm volatile("v_mbcnt_lo_u32_b32 %0, -1, 0\n\tv_mbcnt_hi_u32_b32 %0, -1, %0" : "=v"(t)); return wv * 64 + t; }
; DEVI void gbar(unsigned* ctr, unsigned& gen, int wv) {
;   asm volatile("s_waitcnt vmcnt(0) lgkmcnt(0)" ::: "memory");
;   __syncthreads();
;   ++gen;
;   const int tb = opaque_tid(wv);
;   if (tb < 64) {
;     __builtin_amdgcn_fence(__ATOMIC_RELEASE, "agent");
;     asm volatile("s_waitcnt vmcnt(0)" ::: "memory");
;     if (tb == 0) {
;       __hip_atomic_fetch_add(ctr, 1u, __ATOMIC_RELAXED, __HIP_MEMORY_SCOPE_AGENT);
;       const unsigned target = gen * 256u;
;       while (__hip_atomic_load(ctr, __ATOMIC_RELAXED, __HIP_MEMORY_SCOPE_AGENT) < target) { }
;     }
;     __builtin_amdgcn_fence(__ATOMIC_ACQUIRE, "agent");
;     asm volatile("s_waitcnt vmcnt(0)" ::: "memory");
;   }
;   __syncthreads();
.LBB0_1745:
	s_waitcnt lgkmcnt(0)
	s_barrier
	s_waitcnt vmcnt(0) lgkmcnt(0)
	s_barrier
	v_mbcnt_lo_u32_b32 v0, -1, 0
	v_mbcnt_hi_u32_b32 v0, -1, v0
	v_readlane_b32 s2, v252, 46
	s_nop 1
	v_add_u32_e32 v0, s2, v0
	v_cmp_gt_i32_e32 vcc, 64, v0
	s_and_saveexec_b64 s[4:5], vcc
	s_cbranch_execz .LBB0_1752
	s_waitcnt vmcnt(0)
	v_cmp_eq_u32_e32 vcc, 0, v0
	s_and_saveexec_b64 s[6:7], vcc
	s_cbranch_execz .LBB0_1751
	s_getreg_b32 s12, hwreg(HW_REG_XCC_ID, 0, 4)
	s_lshl_b32 s12, s12, 2
	s_add_u32 s12, s52, s12
	s_addc_u32 s13, s53, 0
	v_mov_b32_e32 v0, 1
	global_atomic_add v0, v33, v0, s[12:13] offset:128 sc0
	v_readlane_b32 s2, v254, 48
	s_lshl_b32 s2, s2, 5
	s_addk_i32 s2, 128
	s_waitcnt vmcnt(0)
	v_readfirstlane_b32 s10, v0
	s_add_i32 s10, s10, 1
	s_cmp_lg_u32 s10, s2
	s_cbranch_scc1 .Lgb4_poll
	buffer_wbl2 sc1
	s_waitcnt vmcnt(0)
	v_mov_b32_e32 v0, 1
	global_atomic_add v33, v0, s[52:53]

; DEVI int opaque_tid(int wv) { int t; asm volatile("v_mbcnt_lo_u32_b32 %0, -1, 0\n\tv_mbcnt_hi_u32_b32 %0, -1, %0" : "=v"(t)); return wv * 64 + t; }
; DEVI void gbar(unsigned* ctr, unsigned& gen, int wv) {
;   asm volatile("s_waitcnt vmcnt(0) lgkmcnt(0)" ::: "memory");
;   __syncthreads();
;   ++gen;
;   const int tb = opaque_tid(wv);
;   if (tb < 64) {
;     __builtin_amdgcn_fence(__ATOMIC_RELEASE, "agent");
;     asm volatile("s_waitcnt vmcnt(0)" ::: "memory");
;     if (tb == 0) {
;       __hip_atomic_fetch_add(ctr, 1u, __ATOMIC_RELAXED, __HIP_MEMORY_SCOPE_AGENT);
;       const unsigned target = gen * 256u;
;       while (__hip_atomic_load(ctr, __ATOMIC_RELAXED, __HIP_MEMORY_SCOPE_AGENT) < target) { }
;     }
;     __builtin_amdgcn_fence(__ATOMIC_ACQUIRE, "agent");
;     asm volatile("s_waitcnt vmcnt(0)" ::: "memory");
;   }
;   __syncthreads();
.LBB0_1978:
	s_barrier
	s_waitcnt vmcnt(0) lgkmcnt(0)
	s_barrier
	v_mbcnt_lo_u32_b32 v0, -1, 0
	v_mbcnt_hi_u32_b32 v0, -1, v0
	v_readlane_b32 s2, v252, 46
	s_nop 1
	v_add_u32_e32 v0, s2, v0
	v_cmp_gt_i32_e32 vcc, 64, v0
	s_and_saveexec_b64 s[4:5], vcc
	s_cbranch_execz .LBB0_1985
	s_waitcnt vmcnt(0)
	v_cmp_eq_u32_e32 vcc, 0, v0
	s_and_saveexec_b64 s[6:7], vcc
	s_cbranch_execz .LBB0_1984
	s_getreg_b32 s14, hwreg(HW_REG_XCC_ID, 0, 4)
	s_lshl_b32 s14, s14, 2
	s_add_u32 s14, s52, s14
	s_addc_u32 s15, s53, 0
	v_mov_b32_e32 v0, 1
	global_atomic_add v0, v33, v0, s[14:15] offset:128 sc0
	v_readlane_b32 s2, v254, 48
	s_lshl_b32 s2, s2, 5
	s_addk_i32 s2, 160
	s_waitcnt vmcnt(0)
	v_readfirstlane_b32 s8, v0
	s_add_i32 s8, s8, 1
	s_cmp_lg_u32 s8, s2
	s_cbranch_scc1 .Lgb5_poll
	buffer_wbl2 sc1
	s_waitcnt vmcnt(0)
	v_mov_b32_e32 v0, 1
	global_atomic_add v33, v0, s[52:53]

; DEVI int opaque_tid(int wv) { int t; asm volatile("v_mbcnt_lo_u32_b32 %0, -1, 0\n\tv_mbcnt_hi_u32_b32 %0, -1, %0" : "=v"(t)); return wv * 64 + t; }
; DEVI void gbar(unsigned* ctr, unsigned& gen, int wv) {
;   asm volatile("s_waitcnt vmcnt(0) lgkmcnt(0)" ::: "memory");
;   __syncthreads();
;   ++gen;
;   const int tb = opaque_tid(wv);
;   if (tb < 64) {
;     __builtin_amdgcn_fence(__ATOMIC_RELEASE, "agent");
;     asm volatile("s_waitcnt vmcnt(0)" ::: "memory");
;     if (tb == 0) {
.LBB0_2236:
	s_waitcnt vmcnt(0)
	v_cmp_eq_u32_e32 vcc, 0, v0
	s_and_saveexec_b64 s[4:5], vcc
	s_cbranch_execnz .LBB0_2237
	s_getpc_b64 s[98:99]

; DEVI void gbar(unsigned* ctr, unsigned& gen, int wv) {
;     ...
;     if (tb == 0) {
;       __hip_atomic_fetch_add(ctr, 1u, __ATOMIC_RELAXED, __HIP_MEMORY_SCOPE_AGENT);
;       const unsigned target = gen * 256u;
;       while (__hip_atomic_load(ctr, __ATOMIC_RELAXED, __HIP_MEMORY_SCOPE_AGENT) < target) { }
.LBB0_2237:
	s_getreg_b32 s8, hwreg(HW_REG_XCC_ID, 0, 4)
	s_lshl_b32 s8, s8, 2
	s_add_u32 s8, s52, s8
	s_addc_u32 s9, s53, 0
	v_mov_b32_e32 v0, 1
	global_atomic_add v0, v33, v0, s[8:9] offset:128 sc0
	v_readlane_b32 s2, v254, 48
	s_lshl_b32 s2, s2, 5
	s_waitcnt vmcnt(0)
	v_readfirstlane_b32 s6, v0
	s_add_i32 s6, s6, 1
	s_cmp_lg_u32 s6, s2
	s_cbranch_scc1 .Lgb6_poll
	buffer_wbl2 sc1
	s_waitcnt vmcnt(0)
	v_mov_b32_e32 v0, 1
	global_atomic_add v33, v0, s[52:53]
